# in-proj epilogue: rope cos/sin fragments loaded once per row group and shared by both column halves (8 fewer load+store-drain waits per rope tile)
# speedup vs baseline: 1.0197x; 1.0076x over previous
.LBB0_310:
	s_add_u32 s0, s18, 0xfffc0080
	s_addc_u32 s1, s19, -1
	s_add_i32 s27, 0, 0x10000
	v_add_u32_e32 v147, s27, v139
	ds_read_b128 v[152:155], v147
	ds_read_b128 v[156:159], v147 offset:1024
	ds_read_b128 v[160:163], v147 offset:2048
	ds_read_b128 v[164:167], v147 offset:3072
	s_cmp_eq_u32 s26, 12
	s_cselect_b32 s17, s3, s1
	s_cselect_b32 s16, s13, s0
	s_cselect_b32 s1, s20, s25
	s_cselect_b32 s0, s21, s24
	v_lshl_add_u64 v[190:191], s[18:19], 0, v[142:143]
	s_add_i32 m0, s95, 0xc000
	ds_read_b128 v[168:171], v181
	ds_read_b128 v[172:175], v181 offset:1024
	ds_read_b128 v[176:179], v181 offset:2048
	ds_read_b128 v[182:185], v181 offset:3072
	ds_read_b128 v[186:189], v181 offset:4096
	ds_read_b128 v[202:205], v181 offset:5120
	ds_read_b128 v[206:209], v181 offset:6144
	ds_read_b128 v[210:213], v181 offset:7168
	global_load_lds_dwordx4 v[190:191], off
	v_lshl_add_u64 v[190:191], s[18:19], 0, v[144:145]
	s_add_i32 m0, s95, 0xe000
	s_nop 0
	global_load_lds_dwordx4 v[190:191], off
	s_waitcnt lgkmcnt(8)
	s_barrier
	s_waitcnt lgkmcnt(0)
	s_setprio 1
	s_waitcnt lgkmcnt(0)
	v_mfma_f32_16x16x32_bf16 v[124:127], v[152:155], v[168:171], v[124:127]
	v_mfma_f32_16x16x32_bf16 v[120:123], v[160:163], v[168:171], v[120:123]
	v_mfma_f32_16x16x32_bf16 v[108:111], v[152:155], v[176:179], v[108:111]
	v_mfma_f32_16x16x32_bf16 v[104:107], v[160:163], v[176:179], v[104:107]
	v_mfma_f32_16x16x32_bf16 v[92:95], v[152:155], v[186:189], v[92:95]
	v_mfma_f32_16x16x32_bf16 v[88:91], v[160:163], v[186:189], v[88:91]
	v_mfma_f32_16x16x32_bf16 v[76:79], v[152:155], v[206:209], v[76:79]
	v_mfma_f32_16x16x32_bf16 v[72:75], v[160:163], v[206:209], v[72:75]
	v_mfma_f32_16x16x32_bf16 v[124:127], v[156:159], v[172:175], v[124:127]
	v_mfma_f32_16x16x32_bf16 v[120:123], v[164:167], v[172:175], v[120:123]
	v_mfma_f32_16x16x32_bf16 v[108:111], v[156:159], v[182:185], v[108:111]
	v_mfma_f32_16x16x32_bf16 v[104:107], v[164:167], v[182:185], v[104:107]
	v_mfma_f32_16x16x32_bf16 v[92:95], v[156:159], v[202:205], v[92:95]
	v_mfma_f32_16x16x32_bf16 v[88:91], v[164:167], v[202:205], v[88:91]
	v_mfma_f32_16x16x32_bf16 v[76:79], v[156:159], v[210:213], v[76:79]
	v_mfma_f32_16x16x32_bf16 v[72:75], v[164:167], v[210:213], v[72:75]
	s_setprio 0
	s_barrier
	s_add_i32 s36, 0, 0x14000
	s_add_i32 s27, s27, s94
	v_add_u32_e32 v147, s36, v139
	v_lshl_add_u64 v[190:191], s[0:1], 0, v[132:133]
	s_mov_b32 m0, s27
	ds_read_b128 v[214:217], v147
	ds_read_b128 v[218:221], v147 offset:1024
	ds_read_b128 v[238:241], v147 offset:2048
	ds_read_b128 v[242:245], v147 offset:3072
	global_load_lds_dwordx4 v[190:191], off
	v_lshl_add_u64 v[222:223], s[0:1], 0, v[128:129]
	s_add_i32 m0, s27, 0x2000
	s_nop 0
	global_load_lds_dwordx4 v[222:223], off
	s_barrier
	s_waitcnt lgkmcnt(0)
	s_setprio 1
	s_waitcnt lgkmcnt(0)
	v_mfma_f32_16x16x32_bf16 v[116:119], v[214:217], v[168:171], v[116:119]
	v_mfma_f32_16x16x32_bf16 v[112:115], v[238:241], v[168:171], v[112:115]
	v_mfma_f32_16x16x32_bf16 v[100:103], v[214:217], v[176:179], v[100:103]
	v_mfma_f32_16x16x32_bf16 v[96:99], v[238:241], v[176:179], v[96:99]
	v_mfma_f32_16x16x32_bf16 v[84:87], v[214:217], v[186:189], v[84:87]
	v_mfma_f32_16x16x32_bf16 v[80:83], v[238:241], v[186:189], v[80:83]
	v_mfma_f32_16x16x32_bf16 v[68:71], v[214:217], v[206:209], v[68:71]
	v_mfma_f32_16x16x32_bf16 v[64:67], v[238:241], v[206:209], v[64:67]
	v_mfma_f32_16x16x32_bf16 v[116:119], v[218:221], v[172:175], v[116:119]
	v_mfma_f32_16x16x32_bf16 v[112:115], v[242:245], v[172:175], v[112:115]
	v_mfma_f32_16x16x32_bf16 v[100:103], v[218:221], v[182:185], v[100:103]
	v_mfma_f32_16x16x32_bf16 v[96:99], v[242:245], v[182:185], v[96:99]
	v_mfma_f32_16x16x32_bf16 v[84:87], v[218:221], v[202:205], v[84:87]
	v_mfma_f32_16x16x32_bf16 v[80:83], v[242:245], v[202:205], v[80:83]
	v_mfma_f32_16x16x32_bf16 v[68:71], v[218:221], v[210:213], v[68:71]
	v_mfma_f32_16x16x32_bf16 v[64:67], v[242:245], v[210:213], v[64:67]
	s_setprio 0
	s_mov_b32 m0, s95
	v_lshl_add_u64 v[246:247], s[16:17], 0, v[134:135]
	s_barrier
	ds_read_b128 v[168:171], v181 offset:16384
	ds_read_b128 v[172:175], v181 offset:17408
	ds_read_b128 v[176:179], v181 offset:18432
	ds_read_b128 v[182:185], v181 offset:19456
	ds_read_b128 v[186:189], v181 offset:20480
	ds_read_b128 v[202:205], v181 offset:21504
	ds_read_b128 v[206:209], v181 offset:22528
	ds_read_b128 v[210:213], v181 offset:23552
	global_load_lds_dwordx4 v[246:247], off
	v_lshl_add_u64 v[248:249], s[16:17], 0, v[130:131]
	s_mov_b32 m0, s96
	s_nop 0
	global_load_lds_dwordx4 v[248:249], off
	s_barrier
	s_waitcnt lgkmcnt(0)
	s_setprio 1
	s_waitcnt lgkmcnt(0)
	v_mfma_f32_16x16x32_bf16 v[60:63], v[152:155], v[168:171], v[60:63]
	v_mfma_f32_16x16x32_bf16 v[56:59], v[160:163], v[168:171], v[56:59]
	v_mfma_f32_16x16x32_bf16 v[44:47], v[152:155], v[176:179], v[44:47]
	v_mfma_f32_16x16x32_bf16 v[40:43], v[160:163], v[176:179], v[40:43]
	v_mfma_f32_16x16x32_bf16 v[28:31], v[152:155], v[186:189], v[28:31]
	v_mfma_f32_16x16x32_bf16 v[24:27], v[160:163], v[186:189], v[24:27]
	v_mfma_f32_16x16x32_bf16 v[12:15], v[152:155], v[206:209], v[12:15]
	v_mfma_f32_16x16x32_bf16 v[8:11], v[160:163], v[206:209], v[8:11]
	v_mfma_f32_16x16x32_bf16 v[60:63], v[156:159], v[172:175], v[60:63]
	v_mfma_f32_16x16x32_bf16 v[56:59], v[164:167], v[172:175], v[56:59]
	v_mfma_f32_16x16x32_bf16 v[44:47], v[156:159], v[182:185], v[44:47]
	v_mfma_f32_16x16x32_bf16 v[40:43], v[164:167], v[182:185], v[40:43]
	v_mfma_f32_16x16x32_bf16 v[28:31], v[156:159], v[202:205], v[28:31]
	v_mfma_f32_16x16x32_bf16 v[24:27], v[164:167], v[202:205], v[24:27]
	v_mfma_f32_16x16x32_bf16 v[12:15], v[156:159], v[210:213], v[12:15]
	v_mfma_f32_16x16x32_bf16 v[8:11], v[164:167], v[210:213], v[8:11]
	s_setprio 0
	s_barrier
	s_add_u32 s28, s0, 0x40000
	s_addc_u32 s29, s1, 0
	s_add_i32 s27, s36, s94
	v_lshl_add_u64 v[152:153], s[28:29], 0, v[132:133]
	s_mov_b32 m0, s27
	s_nop 0
	global_load_lds_dwordx4 v[152:153], off
	v_lshl_add_u64 v[152:153], s[28:29], 0, v[128:129]
	s_add_i32 m0, s27, 0x2000
	s_nop 0
	global_load_lds_dwordx4 v[152:153], off
	s_waitcnt vmcnt(6)
	s_barrier
	s_setprio 1
	v_mfma_f32_16x16x32_bf16 v[52:55], v[214:217], v[168:171], v[52:55]
	v_mfma_f32_16x16x32_bf16 v[48:51], v[238:241], v[168:171], v[48:51]
	v_mfma_f32_16x16x32_bf16 v[36:39], v[214:217], v[176:179], v[36:39]
	v_mfma_f32_16x16x32_bf16 v[32:35], v[238:241], v[176:179], v[32:35]
	v_mfma_f32_16x16x32_bf16 v[20:23], v[214:217], v[186:189], v[20:23]
	v_mfma_f32_16x16x32_bf16 v[16:19], v[238:241], v[186:189], v[16:19]
	v_mfma_f32_16x16x32_bf16 v[4:7], v[214:217], v[206:209], v[4:7]
	v_mfma_f32_16x16x32_bf16 v[0:3], v[238:241], v[206:209], v[0:3]
	v_mfma_f32_16x16x32_bf16 v[52:55], v[218:221], v[172:175], v[52:55]
	v_mfma_f32_16x16x32_bf16 v[48:51], v[242:245], v[172:175], v[48:51]
	v_mfma_f32_16x16x32_bf16 v[36:39], v[218:221], v[182:185], v[36:39]
	v_mfma_f32_16x16x32_bf16 v[32:35], v[242:245], v[182:185], v[32:35]
	v_mfma_f32_16x16x32_bf16 v[20:23], v[218:221], v[202:205], v[20:23]
	v_mfma_f32_16x16x32_bf16 v[16:19], v[242:245], v[202:205], v[16:19]
	v_mfma_f32_16x16x32_bf16 v[4:7], v[218:221], v[210:213], v[4:7]
	v_mfma_f32_16x16x32_bf16 v[0:3], v[242:245], v[210:213], v[0:3]
	s_setprio 0
	s_add_i32 s27, 0, 0x18000
	v_add_u32_e32 v147, s27, v139
	s_barrier
	ds_read_b128 v[152:155], v147
	ds_read_b128 v[156:159], v147 offset:1024
	ds_read_b128 v[160:163], v147 offset:2048
	ds_read_b128 v[164:167], v147 offset:3072
	s_add_u32 s16, s16, 0x40000
	s_addc_u32 s17, s17, 0
	s_mov_b32 m0, s97
	v_lshl_add_u64 v[214:215], s[16:17], 0, v[134:135]
	ds_read_b128 v[168:171], v181 offset:32768
	ds_read_b128 v[172:175], v181 offset:33792
	ds_read_b128 v[176:179], v181 offset:34816
	ds_read_b128 v[182:185], v181 offset:35840
	ds_read_b128 v[186:189], v181 offset:36864
	ds_read_b128 v[202:205], v181 offset:37888
	ds_read_b128 v[206:209], v181 offset:38912
	ds_read_b128 v[210:213], v181 offset:39936
	global_load_lds_dwordx4 v[214:215], off
	v_lshl_add_u64 v[214:215], s[16:17], 0, v[130:131]
	s_mov_b32 m0, s4
	s_nop 0
	global_load_lds_dwordx4 v[214:215], off
	s_waitcnt lgkmcnt(8)
	s_barrier
	s_waitcnt lgkmcnt(0)
	s_setprio 1
	s_waitcnt lgkmcnt(0)
	v_mfma_f32_16x16x32_bf16 v[124:127], v[152:155], v[168:171], v[124:127]
	v_mfma_f32_16x16x32_bf16 v[120:123], v[160:163], v[168:171], v[120:123]
	v_mfma_f32_16x16x32_bf16 v[108:111], v[152:155], v[176:179], v[108:111]
	v_mfma_f32_16x16x32_bf16 v[104:107], v[160:163], v[176:179], v[104:107]
	v_mfma_f32_16x16x32_bf16 v[92:95], v[152:155], v[186:189], v[92:95]
	v_mfma_f32_16x16x32_bf16 v[88:91], v[160:163], v[186:189], v[88:91]
	v_mfma_f32_16x16x32_bf16 v[76:79], v[152:155], v[206:209], v[76:79]
	v_mfma_f32_16x16x32_bf16 v[72:75], v[160:163], v[206:209], v[72:75]
	v_mfma_f32_16x16x32_bf16 v[124:127], v[156:159], v[172:175], v[124:127]
	v_mfma_f32_16x16x32_bf16 v[120:123], v[164:167], v[172:175], v[120:123]
	v_mfma_f32_16x16x32_bf16 v[108:111], v[156:159], v[182:185], v[108:111]
	v_mfma_f32_16x16x32_bf16 v[104:107], v[164:167], v[182:185], v[104:107]
	v_mfma_f32_16x16x32_bf16 v[92:95], v[156:159], v[202:205], v[92:95]
	v_mfma_f32_16x16x32_bf16 v[88:91], v[164:167], v[202:205], v[88:91]
	v_mfma_f32_16x16x32_bf16 v[76:79], v[156:159], v[210:213], v[76:79]
	v_mfma_f32_16x16x32_bf16 v[72:75], v[164:167], v[210:213], v[72:75]
	s_setprio 0
	s_barrier
	s_add_i32 s16, 0, 0x1c000
	s_add_i32 s17, s27, s94
	v_add_u32_e32 v147, s16, v139
	v_lshl_add_u64 v[190:191], v[190:191], 0, s[30:31]
	s_mov_b32 m0, s17
	ds_read_b128 v[214:217], v147
	ds_read_b128 v[218:221], v147 offset:1024
	ds_read_b128 v[238:241], v147 offset:2048
	ds_read_b128 v[242:245], v147 offset:3072
	global_load_lds_dwordx4 v[190:191], off
	v_lshl_add_u64 v[190:191], v[222:223], 0, s[30:31]
	s_add_i32 m0, s17, 0x2000
	s_nop 0
	global_load_lds_dwordx4 v[190:191], off
	s_barrier
	s_waitcnt lgkmcnt(0)
	s_setprio 1
	s_waitcnt lgkmcnt(0)
	v_mfma_f32_16x16x32_bf16 v[116:119], v[214:217], v[168:171], v[116:119]
	v_mfma_f32_16x16x32_bf16 v[112:115], v[238:241], v[168:171], v[112:115]
	v_mfma_f32_16x16x32_bf16 v[100:103], v[214:217], v[176:179], v[100:103]
	v_mfma_f32_16x16x32_bf16 v[96:99], v[238:241], v[176:179], v[96:99]
	v_mfma_f32_16x16x32_bf16 v[84:87], v[214:217], v[186:189], v[84:87]
	v_mfma_f32_16x16x32_bf16 v[80:83], v[238:241], v[186:189], v[80:83]
	v_mfma_f32_16x16x32_bf16 v[68:71], v[214:217], v[206:209], v[68:71]
	v_mfma_f32_16x16x32_bf16 v[64:67], v[238:241], v[206:209], v[64:67]
	v_mfma_f32_16x16x32_bf16 v[116:119], v[218:221], v[172:175], v[116:119]
	v_mfma_f32_16x16x32_bf16 v[112:115], v[242:245], v[172:175], v[112:115]
	v_mfma_f32_16x16x32_bf16 v[100:103], v[218:221], v[182:185], v[100:103]
	v_mfma_f32_16x16x32_bf16 v[96:99], v[242:245], v[182:185], v[96:99]
	v_mfma_f32_16x16x32_bf16 v[84:87], v[218:221], v[202:205], v[84:87]
	v_mfma_f32_16x16x32_bf16 v[80:83], v[242:245], v[202:205], v[80:83]
	v_mfma_f32_16x16x32_bf16 v[68:71], v[218:221], v[210:213], v[68:71]
	v_mfma_f32_16x16x32_bf16 v[64:67], v[242:245], v[210:213], v[64:67]
	s_setprio 0
	s_mov_b32 m0, s6
	v_lshl_add_u64 v[190:191], v[246:247], 0, s[30:31]
	s_barrier
	ds_read_b128 v[168:171], v181 offset:49152
	ds_read_b128 v[172:175], v181 offset:50176
	ds_read_b128 v[176:179], v181 offset:51200
	ds_read_b128 v[182:185], v181 offset:52224
	ds_read_b128 v[186:189], v181 offset:53248
	ds_read_b128 v[202:205], v181 offset:54272
	ds_read_b128 v[206:209], v181 offset:55296
	ds_read_b128 v[210:213], v181 offset:56320
	global_load_lds_dwordx4 v[190:191], off
	v_lshl_add_u64 v[190:191], v[248:249], 0, s[30:31]
	s_mov_b32 m0, s7
	s_nop 0
	global_load_lds_dwordx4 v[190:191], off
	s_barrier
	s_waitcnt lgkmcnt(0)
	s_setprio 1
	s_waitcnt lgkmcnt(0)
	v_mfma_f32_16x16x32_bf16 v[60:63], v[152:155], v[168:171], v[60:63]
	v_mfma_f32_16x16x32_bf16 v[56:59], v[160:163], v[168:171], v[56:59]
	v_mfma_f32_16x16x32_bf16 v[44:47], v[152:155], v[176:179], v[44:47]
	v_mfma_f32_16x16x32_bf16 v[40:43], v[160:163], v[176:179], v[40:43]
	v_mfma_f32_16x16x32_bf16 v[28:31], v[152:155], v[186:189], v[28:31]
	v_mfma_f32_16x16x32_bf16 v[24:27], v[160:163], v[186:189], v[24:27]
	v_mfma_f32_16x16x32_bf16 v[12:15], v[152:155], v[206:209], v[12:15]
	v_mfma_f32_16x16x32_bf16 v[8:11], v[160:163], v[206:209], v[8:11]
	v_mfma_f32_16x16x32_bf16 v[60:63], v[156:159], v[172:175], v[60:63]
	v_mfma_f32_16x16x32_bf16 v[56:59], v[164:167], v[172:175], v[56:59]
	v_mfma_f32_16x16x32_bf16 v[44:47], v[156:159], v[182:185], v[44:47]
	v_mfma_f32_16x16x32_bf16 v[40:43], v[164:167], v[182:185], v[40:43]
	v_mfma_f32_16x16x32_bf16 v[28:31], v[156:159], v[202:205], v[28:31]
	v_mfma_f32_16x16x32_bf16 v[24:27], v[164:167], v[202:205], v[24:27]
	v_mfma_f32_16x16x32_bf16 v[12:15], v[156:159], v[210:213], v[12:15]
	v_mfma_f32_16x16x32_bf16 v[8:11], v[164:167], v[210:213], v[8:11]
	s_setprio 0
	s_barrier
	s_add_u32 s0, s0, 0x40080
	s_addc_u32 s1, s1, 0
	s_add_i32 s16, s16, s94
	v_lshl_add_u64 v[152:153], s[0:1], 0, v[132:133]
	s_mov_b32 m0, s16
	s_nop 0
	global_load_lds_dwordx4 v[152:153], off
	v_lshl_add_u64 v[152:153], s[0:1], 0, v[128:129]
	s_add_i32 m0, s16, 0x2000
	s_nop 0
	global_load_lds_dwordx4 v[152:153], off
	s_waitcnt vmcnt(6)
	s_barrier
	s_setprio 1
	v_mfma_f32_16x16x32_bf16 v[52:55], v[214:217], v[168:171], v[52:55]
	v_mfma_f32_16x16x32_bf16 v[48:51], v[238:241], v[168:171], v[48:51]
	v_mfma_f32_16x16x32_bf16 v[36:39], v[214:217], v[176:179], v[36:39]
	v_mfma_f32_16x16x32_bf16 v[32:35], v[238:241], v[176:179], v[32:35]
	v_mfma_f32_16x16x32_bf16 v[20:23], v[214:217], v[186:189], v[20:23]
	v_mfma_f32_16x16x32_bf16 v[16:19], v[238:241], v[186:189], v[16:19]
	v_mfma_f32_16x16x32_bf16 v[4:7], v[214:217], v[206:209], v[4:7]
	v_mfma_f32_16x16x32_bf16 v[0:3], v[238:241], v[206:209], v[0:3]
	v_mfma_f32_16x16x32_bf16 v[52:55], v[218:221], v[172:175], v[52:55]
	v_mfma_f32_16x16x32_bf16 v[48:51], v[242:245], v[172:175], v[48:51]
	v_mfma_f32_16x16x32_bf16 v[36:39], v[218:221], v[182:185], v[36:39]
	v_mfma_f32_16x16x32_bf16 v[32:35], v[242:245], v[182:185], v[32:35]
	v_mfma_f32_16x16x32_bf16 v[20:23], v[218:221], v[202:205], v[20:23]
	v_mfma_f32_16x16x32_bf16 v[16:19], v[242:245], v[202:205], v[16:19]
	v_mfma_f32_16x16x32_bf16 v[4:7], v[218:221], v[210:213], v[4:7]
	v_mfma_f32_16x16x32_bf16 v[0:3], v[242:245], v[210:213], v[0:3]
	s_setprio 0
	s_add_i32 s26, s26, 2
	s_add_u32 s18, s18, 0x100
	s_addc_u32 s19, s19, 0
	s_add_u32 s24, s24, 0x100
	s_addc_u32 s25, s25, 0
	s_cmp_gt_u32 s26, 13
	s_barrier
	s_cbranch_scc0 .LBB0_310
	s_cmp_lt_i32 s2, 64
	s_cselect_b64 s[44:45], -1, 0
	s_lshl_b32 s26, s2, 8
	s_add_i32 s26, s26, s5
	s_add_i32 s0, s33, -2
	s_cmp_lt_u32 s0, 4
	s_mov_b64 s[24:25], s[66:67]
	s_cselect_b64 s[50:51], -1, 0
	s_cmp_gt_u32 s33, 3
	v_lshlrev_b32_e32 v162, 2, v138
	v_mov_b32_e32 v163, v197
	s_cselect_b64 s[42:43], -1, 0
	s_cmp_gt_u32 s0, 3
	v_lshl_add_u64 v[152:153], s[24:25], 0, v[162:163]
	s_mov_b64 s[0:1], 0x4500000
	v_bitop3_b32 v151, s26, v229, v137 bitop3:0xc8
	v_lshl_add_u64 v[156:157], v[152:153], 0, s[0:1]
	s_mov_b64 s[0:1], 0x4580800
	v_cndmask_b32_e64 v147, v141, v151, s[44:45]
	v_lshl_add_u64 v[154:155], v[152:153], 0, s[0:1]
	v_lshlrev_b32_e32 v196, 8, v147
	s_mov_b64 s[18:19], s[10:11]
	s_mov_b64 s[52:53], s[60:61]
	v_lshl_add_u64 v[170:171], v[156:157], 0, v[196:197]
	v_lshl_add_u64 v[172:173], v[154:155], 0, v[196:197]
	s_cbranch_scc1 .LBB0_313
	global_load_dwordx4 v[202:205], v[172:173], off
	global_load_dwordx4 v[206:209], v[170:171], off
	s_waitcnt vmcnt(0)
	v_pk_mul_f32 v[152:153], v[122:123], v[204:205]
	v_pk_mul_f32 v[168:169], v[120:121], v[202:203]
	v_pk_mul_f32 v[160:161], v[126:127], v[204:205]
	v_pk_mul_f32 v[158:159], v[124:125], v[202:203]
	v_pk_fma_f32 v[126:127], v[126:127], v[208:209], v[152:153] neg_lo:[0,0,1] neg_hi:[0,0,1]
	v_pk_fma_f32 v[124:125], v[124:125], v[206:207], v[168:169] neg_lo:[0,0,1] neg_hi:[0,0,1]
	v_pk_fma_f32 v[122:123], v[122:123], v[208:209], v[160:161]
	v_pk_fma_f32 v[120:121], v[120:121], v[206:207], v[158:159]
	v_pk_mul_f32 v[152:153], v[124:125], s[14:15] op_sel_hi:[1,0]
	v_pk_mul_f32 v[158:159], v[126:127], s[14:15] op_sel_hi:[1,0]
	v_pk_mul_f32 v[160:161], v[120:121], s[14:15] op_sel_hi:[1,0]
	v_pk_mul_f32 v[164:165], v[122:123], s[14:15] op_sel_hi:[1,0]
	v_cndmask_b32_e64 v121, v121, v161, s[42:43]
	v_cndmask_b32_e64 v123, v123, v165, s[42:43]
	v_cndmask_b32_e64 v122, v122, v164, s[42:43]
	v_cndmask_b32_e64 v120, v120, v160, s[42:43]
	v_cndmask_b32_e64 v127, v127, v159, s[42:43]
	v_cndmask_b32_e64 v126, v126, v158, s[42:43]
	v_cndmask_b32_e64 v125, v125, v153, s[42:43]
	v_cndmask_b32_e64 v124, v124, v152, s[42:43]

.LBB0_329:
	s_nop 1
	v_cndmask_b32_e64 v120, 0, 1, s[50:51]
	v_cmp_ne_u32_e64 s[52:53], 1, v120
	s_andn2_b64 vcc, exec, s[50:51]
	s_cbranch_vccnz .LBB0_331
	v_pk_mul_f32 v[170:171], v[114:115], v[204:205]
	v_pk_mul_f32 v[172:173], v[112:113], v[202:203]
	v_pk_mul_f32 v[122:123], v[118:119], v[204:205]
	v_pk_mul_f32 v[120:121], v[116:117], v[202:203]
	v_pk_fma_f32 v[118:119], v[118:119], v[208:209], v[170:171] neg_lo:[0,0,1] neg_hi:[0,0,1]
	v_pk_fma_f32 v[116:117], v[116:117], v[206:207], v[172:173] neg_lo:[0,0,1] neg_hi:[0,0,1]
	v_pk_fma_f32 v[114:115], v[114:115], v[208:209], v[122:123]
	v_pk_fma_f32 v[112:113], v[112:113], v[206:207], v[120:121]
	v_pk_mul_f32 v[120:121], v[116:117], s[14:15] op_sel_hi:[1,0]
	v_pk_mul_f32 v[122:123], v[118:119], s[14:15] op_sel_hi:[1,0]
	v_pk_mul_f32 v[124:125], v[112:113], s[14:15] op_sel_hi:[1,0]
	v_pk_mul_f32 v[126:127], v[114:115], s[14:15] op_sel_hi:[1,0]
	v_cndmask_b32_e64 v113, v113, v125, s[42:43]
	v_cndmask_b32_e64 v115, v115, v127, s[42:43]
	v_cndmask_b32_e64 v114, v114, v126, s[42:43]
	v_cndmask_b32_e64 v112, v112, v124, s[42:43]
	v_cndmask_b32_e64 v119, v119, v123, s[42:43]
	v_cndmask_b32_e64 v118, v118, v122, s[42:43]
	v_cndmask_b32_e64 v117, v117, v121, s[42:43]
	v_cndmask_b32_e64 v116, v116, v120, s[42:43]

.LBB0_338:
	s_or_b32 s2, s26, 16
	v_bitop3_b32 v151, s2, v233, v137 bitop3:0xc8
	v_cndmask_b32_e64 v112, v141, v151, s[44:45]
	v_lshlrev_b32_e32 v196, 8, v112
	v_lshl_add_u64 v[118:119], v[156:157], 0, v[196:197]
	s_and_b64 vcc, exec, s[52:53]
	v_lshl_add_u64 v[122:123], v[154:155], 0, v[196:197]
	s_cbranch_vccnz .LBB0_340
	global_load_dwordx4 v[202:205], v[122:123], off
	global_load_dwordx4 v[206:209], v[118:119], off
	s_waitcnt vmcnt(0)
	v_pk_mul_f32 v[116:117], v[106:107], v[204:205]
	v_pk_mul_f32 v[120:121], v[104:105], v[202:203]
	v_pk_mul_f32 v[114:115], v[110:111], v[204:205]
	v_pk_mul_f32 v[112:113], v[108:109], v[202:203]
	v_pk_fma_f32 v[110:111], v[110:111], v[208:209], v[116:117] neg_lo:[0,0,1] neg_hi:[0,0,1]
	v_pk_fma_f32 v[108:109], v[108:109], v[206:207], v[120:121] neg_lo:[0,0,1] neg_hi:[0,0,1]
	v_pk_fma_f32 v[106:107], v[106:107], v[208:209], v[114:115]
	v_pk_fma_f32 v[104:105], v[104:105], v[206:207], v[112:113]
	v_pk_mul_f32 v[112:113], v[108:109], s[14:15] op_sel_hi:[1,0]
	v_pk_mul_f32 v[114:115], v[110:111], s[14:15] op_sel_hi:[1,0]
	v_pk_mul_f32 v[116:117], v[104:105], s[14:15] op_sel_hi:[1,0]
	v_pk_mul_f32 v[120:121], v[106:107], s[14:15] op_sel_hi:[1,0]
	v_cndmask_b32_e64 v105, v105, v117, s[42:43]
	v_cndmask_b32_e64 v107, v107, v121, s[42:43]
	v_cndmask_b32_e64 v106, v106, v120, s[42:43]
	v_cndmask_b32_e64 v104, v104, v116, s[42:43]
	v_cndmask_b32_e64 v111, v111, v115, s[42:43]
	v_cndmask_b32_e64 v110, v110, v114, s[42:43]
	v_cndmask_b32_e64 v109, v109, v113, s[42:43]
	v_cndmask_b32_e64 v108, v108, v112, s[42:43]

.LBB0_356:
	s_and_b64 vcc, exec, s[52:53]
	s_cbranch_vccnz .LBB0_358
	v_pk_mul_f32 v[118:119], v[98:99], v[204:205]
	v_pk_mul_f32 v[122:123], v[96:97], v[202:203]
	v_pk_mul_f32 v[106:107], v[102:103], v[204:205]
	v_pk_mul_f32 v[104:105], v[100:101], v[202:203]
	v_pk_fma_f32 v[102:103], v[102:103], v[208:209], v[118:119] neg_lo:[0,0,1] neg_hi:[0,0,1]
	v_pk_fma_f32 v[100:101], v[100:101], v[206:207], v[122:123] neg_lo:[0,0,1] neg_hi:[0,0,1]
	v_pk_fma_f32 v[98:99], v[98:99], v[208:209], v[106:107]
	v_pk_fma_f32 v[96:97], v[96:97], v[206:207], v[104:105]
	v_pk_mul_f32 v[104:105], v[100:101], s[14:15] op_sel_hi:[1,0]
	v_pk_mul_f32 v[106:107], v[102:103], s[14:15] op_sel_hi:[1,0]
	v_pk_mul_f32 v[108:109], v[96:97], s[14:15] op_sel_hi:[1,0]
	v_pk_mul_f32 v[110:111], v[98:99], s[14:15] op_sel_hi:[1,0]
	v_cndmask_b32_e64 v97, v97, v109, s[42:43]
	v_cndmask_b32_e64 v99, v99, v111, s[42:43]
	v_cndmask_b32_e64 v98, v98, v110, s[42:43]
	v_cndmask_b32_e64 v96, v96, v108, s[42:43]
	v_cndmask_b32_e64 v103, v103, v107, s[42:43]
	v_cndmask_b32_e64 v102, v102, v106, s[42:43]
	v_cndmask_b32_e64 v101, v101, v105, s[42:43]
	v_cndmask_b32_e64 v100, v100, v104, s[42:43]

.LBB0_364:
	s_or_b32 s2, s26, 32
	v_bitop3_b32 v115, s2, v234, v137 bitop3:0xc8
	v_cndmask_b32_e64 v96, v141, v115, s[44:45]
	v_lshlrev_b32_e32 v196, 8, v96
	v_lshl_add_u64 v[102:103], v[156:157], 0, v[196:197]
	s_and_b64 vcc, exec, s[52:53]
	v_lshl_add_u64 v[106:107], v[154:155], 0, v[196:197]
	s_cbranch_vccnz .LBB0_366
	global_load_dwordx4 v[202:205], v[106:107], off
	global_load_dwordx4 v[206:209], v[102:103], off
	s_waitcnt vmcnt(0)
	v_pk_mul_f32 v[100:101], v[90:91], v[204:205]
	v_pk_mul_f32 v[104:105], v[88:89], v[202:203]
	v_pk_mul_f32 v[98:99], v[94:95], v[204:205]
	v_pk_mul_f32 v[96:97], v[92:93], v[202:203]
	v_pk_fma_f32 v[94:95], v[94:95], v[208:209], v[100:101] neg_lo:[0,0,1] neg_hi:[0,0,1]
	v_pk_fma_f32 v[92:93], v[92:93], v[206:207], v[104:105] neg_lo:[0,0,1] neg_hi:[0,0,1]
	v_pk_fma_f32 v[90:91], v[90:91], v[208:209], v[98:99]
	v_pk_fma_f32 v[88:89], v[88:89], v[206:207], v[96:97]
	v_pk_mul_f32 v[96:97], v[92:93], s[14:15] op_sel_hi:[1,0]
	v_pk_mul_f32 v[98:99], v[94:95], s[14:15] op_sel_hi:[1,0]
	v_pk_mul_f32 v[100:101], v[88:89], s[14:15] op_sel_hi:[1,0]
	v_pk_mul_f32 v[104:105], v[90:91], s[14:15] op_sel_hi:[1,0]
	v_cndmask_b32_e64 v89, v89, v101, s[42:43]
	v_cndmask_b32_e64 v91, v91, v105, s[42:43]
	v_cndmask_b32_e64 v90, v90, v104, s[42:43]
	v_cndmask_b32_e64 v88, v88, v100, s[42:43]
	v_cndmask_b32_e64 v95, v95, v99, s[42:43]
	v_cndmask_b32_e64 v94, v94, v98, s[42:43]
	v_cndmask_b32_e64 v93, v93, v97, s[42:43]
	v_cndmask_b32_e64 v92, v92, v96, s[42:43]

.LBB0_382:
	s_and_b64 vcc, exec, s[52:53]
	s_cbranch_vccnz .LBB0_384
	v_pk_mul_f32 v[102:103], v[82:83], v[204:205]
	v_pk_mul_f32 v[106:107], v[80:81], v[202:203]
	v_pk_mul_f32 v[90:91], v[86:87], v[204:205]
	v_pk_mul_f32 v[88:89], v[84:85], v[202:203]
	v_pk_fma_f32 v[86:87], v[86:87], v[208:209], v[102:103] neg_lo:[0,0,1] neg_hi:[0,0,1]
	v_pk_fma_f32 v[84:85], v[84:85], v[206:207], v[106:107] neg_lo:[0,0,1] neg_hi:[0,0,1]
	v_pk_fma_f32 v[82:83], v[82:83], v[208:209], v[90:91]
	v_pk_fma_f32 v[80:81], v[80:81], v[206:207], v[88:89]
	v_pk_mul_f32 v[88:89], v[84:85], s[14:15] op_sel_hi:[1,0]
	v_pk_mul_f32 v[90:91], v[86:87], s[14:15] op_sel_hi:[1,0]
	v_pk_mul_f32 v[92:93], v[80:81], s[14:15] op_sel_hi:[1,0]
	v_pk_mul_f32 v[94:95], v[82:83], s[14:15] op_sel_hi:[1,0]
	v_cndmask_b32_e64 v81, v81, v93, s[42:43]
	v_cndmask_b32_e64 v83, v83, v95, s[42:43]
	v_cndmask_b32_e64 v82, v82, v94, s[42:43]
	v_cndmask_b32_e64 v80, v80, v92, s[42:43]
	v_cndmask_b32_e64 v87, v87, v91, s[42:43]
	v_cndmask_b32_e64 v86, v86, v90, s[42:43]
	v_cndmask_b32_e64 v85, v85, v89, s[42:43]
	v_cndmask_b32_e64 v84, v84, v88, s[42:43]

.LBB0_390:
	s_or_b32 s2, s26, 48
	v_bitop3_b32 v101, s2, v235, v137 bitop3:0xc8
	v_cndmask_b32_e64 v80, v141, v101, s[44:45]
	v_lshlrev_b32_e32 v196, 8, v80
	v_lshl_add_u64 v[88:89], v[156:157], 0, v[196:197]
	s_and_b64 vcc, exec, s[52:53]
	v_lshl_add_u64 v[92:93], v[154:155], 0, v[196:197]
	s_cbranch_vccnz .LBB0_392
	global_load_dwordx4 v[202:205], v[92:93], off
	global_load_dwordx4 v[206:209], v[88:89], off
	s_waitcnt vmcnt(0)
	v_pk_mul_f32 v[90:91], v[74:75], v[204:205]
	v_pk_mul_f32 v[94:95], v[72:73], v[202:203]
	v_pk_mul_f32 v[82:83], v[78:79], v[204:205]
	v_pk_mul_f32 v[80:81], v[76:77], v[202:203]
	v_pk_fma_f32 v[78:79], v[78:79], v[208:209], v[90:91] neg_lo:[0,0,1] neg_hi:[0,0,1]
	v_pk_fma_f32 v[76:77], v[76:77], v[206:207], v[94:95] neg_lo:[0,0,1] neg_hi:[0,0,1]
	v_pk_fma_f32 v[74:75], v[74:75], v[208:209], v[82:83]
	v_pk_fma_f32 v[72:73], v[72:73], v[206:207], v[80:81]
	v_pk_mul_f32 v[80:81], v[76:77], s[14:15] op_sel_hi:[1,0]
	v_pk_mul_f32 v[82:83], v[78:79], s[14:15] op_sel_hi:[1,0]
	v_pk_mul_f32 v[84:85], v[72:73], s[14:15] op_sel_hi:[1,0]
	v_pk_mul_f32 v[86:87], v[74:75], s[14:15] op_sel_hi:[1,0]
	v_cndmask_b32_e64 v73, v73, v85, s[42:43]
	v_cndmask_b32_e64 v75, v75, v87, s[42:43]
	v_cndmask_b32_e64 v74, v74, v86, s[42:43]
	v_cndmask_b32_e64 v72, v72, v84, s[42:43]
	v_cndmask_b32_e64 v79, v79, v83, s[42:43]
	v_cndmask_b32_e64 v78, v78, v82, s[42:43]
	v_cndmask_b32_e64 v77, v77, v81, s[42:43]
	v_cndmask_b32_e64 v76, v76, v80, s[42:43]

.LBB0_408:
	s_or_b64 exec, exec, s[2:3]
	s_and_b64 vcc, exec, s[52:53]
	s_cbranch_vccnz .LBB0_410
	v_pk_mul_f32 v[88:89], v[66:67], v[204:205]
	v_pk_mul_f32 v[92:93], v[64:65], v[202:203]
	v_pk_mul_f32 v[74:75], v[70:71], v[204:205]
	v_pk_mul_f32 v[72:73], v[68:69], v[202:203]
	v_pk_fma_f32 v[70:71], v[70:71], v[208:209], v[88:89] neg_lo:[0,0,1] neg_hi:[0,0,1]
	v_pk_fma_f32 v[68:69], v[68:69], v[206:207], v[92:93] neg_lo:[0,0,1] neg_hi:[0,0,1]
	v_pk_fma_f32 v[66:67], v[66:67], v[208:209], v[74:75]
	v_pk_fma_f32 v[64:65], v[64:65], v[206:207], v[72:73]
	v_pk_mul_f32 v[72:73], v[68:69], s[14:15] op_sel_hi:[1,0]
	v_pk_mul_f32 v[74:75], v[70:71], s[14:15] op_sel_hi:[1,0]
	v_pk_mul_f32 v[76:77], v[64:65], s[14:15] op_sel_hi:[1,0]
	v_pk_mul_f32 v[78:79], v[66:67], s[14:15] op_sel_hi:[1,0]
	v_cndmask_b32_e64 v65, v65, v77, s[42:43]
	v_cndmask_b32_e64 v67, v67, v79, s[42:43]
	v_cndmask_b32_e64 v66, v66, v78, s[42:43]
	v_cndmask_b32_e64 v64, v64, v76, s[42:43]
	v_cndmask_b32_e64 v71, v71, v75, s[42:43]
	v_cndmask_b32_e64 v70, v70, v74, s[42:43]
	v_cndmask_b32_e64 v69, v69, v73, s[42:43]
	v_cndmask_b32_e64 v68, v68, v72, s[42:43]

.LBB0_416:
	s_or_b64 exec, exec, s[2:3]
	s_add_i32 s2, s26, 0x80
	v_bitop3_b32 v85, s2, v229, v137 bitop3:0xc8
	v_cndmask_b32_e64 v64, v141, v85, s[44:45]
	v_lshlrev_b32_e32 v196, 8, v64
	v_lshl_add_u64 v[70:71], v[156:157], 0, v[196:197]
	s_and_b64 vcc, exec, s[52:53]
	v_lshl_add_u64 v[74:75], v[154:155], 0, v[196:197]
	s_cbranch_vccnz .LBB0_418
	global_load_dwordx4 v[202:205], v[74:75], off
	global_load_dwordx4 v[206:209], v[70:71], off
	s_waitcnt vmcnt(0)
	v_pk_mul_f32 v[68:69], v[58:59], v[204:205]
	v_pk_mul_f32 v[72:73], v[56:57], v[202:203]
	v_pk_mul_f32 v[66:67], v[62:63], v[204:205]
	v_pk_mul_f32 v[64:65], v[60:61], v[202:203]
	v_pk_fma_f32 v[62:63], v[62:63], v[208:209], v[68:69] neg_lo:[0,0,1] neg_hi:[0,0,1]
	v_pk_fma_f32 v[60:61], v[60:61], v[206:207], v[72:73] neg_lo:[0,0,1] neg_hi:[0,0,1]
	v_pk_fma_f32 v[58:59], v[58:59], v[208:209], v[66:67]
	v_pk_fma_f32 v[56:57], v[56:57], v[206:207], v[64:65]
	v_pk_mul_f32 v[64:65], v[60:61], s[14:15] op_sel_hi:[1,0]
	v_pk_mul_f32 v[66:67], v[62:63], s[14:15] op_sel_hi:[1,0]
	v_pk_mul_f32 v[68:69], v[56:57], s[14:15] op_sel_hi:[1,0]
	v_pk_mul_f32 v[72:73], v[58:59], s[14:15] op_sel_hi:[1,0]
	v_cndmask_b32_e64 v57, v57, v69, s[42:43]
	v_cndmask_b32_e64 v59, v59, v73, s[42:43]
	v_cndmask_b32_e64 v58, v58, v72, s[42:43]
	v_cndmask_b32_e64 v56, v56, v68, s[42:43]
	v_cndmask_b32_e64 v63, v63, v67, s[42:43]
	v_cndmask_b32_e64 v62, v62, v66, s[42:43]
	v_cndmask_b32_e64 v61, v61, v65, s[42:43]
	v_cndmask_b32_e64 v60, v60, v64, s[42:43]

.LBB0_434:
	s_and_b64 vcc, exec, s[52:53]
	s_cbranch_vccnz .LBB0_436
	v_pk_mul_f32 v[70:71], v[50:51], v[204:205]
	v_pk_mul_f32 v[74:75], v[48:49], v[202:203]
	v_pk_mul_f32 v[58:59], v[54:55], v[204:205]
	v_pk_mul_f32 v[56:57], v[52:53], v[202:203]
	v_pk_fma_f32 v[54:55], v[54:55], v[208:209], v[70:71] neg_lo:[0,0,1] neg_hi:[0,0,1]
	v_pk_fma_f32 v[52:53], v[52:53], v[206:207], v[74:75] neg_lo:[0,0,1] neg_hi:[0,0,1]
	v_pk_fma_f32 v[50:51], v[50:51], v[208:209], v[58:59]
	v_pk_fma_f32 v[48:49], v[48:49], v[206:207], v[56:57]
	v_pk_mul_f32 v[56:57], v[52:53], s[14:15] op_sel_hi:[1,0]
	v_pk_mul_f32 v[58:59], v[54:55], s[14:15] op_sel_hi:[1,0]
	v_pk_mul_f32 v[60:61], v[48:49], s[14:15] op_sel_hi:[1,0]
	v_pk_mul_f32 v[62:63], v[50:51], s[14:15] op_sel_hi:[1,0]
	v_cndmask_b32_e64 v49, v49, v61, s[42:43]
	v_cndmask_b32_e64 v51, v51, v63, s[42:43]
	v_cndmask_b32_e64 v50, v50, v62, s[42:43]
	v_cndmask_b32_e64 v48, v48, v60, s[42:43]
	v_cndmask_b32_e64 v55, v55, v59, s[42:43]
	v_cndmask_b32_e64 v54, v54, v58, s[42:43]
	v_cndmask_b32_e64 v53, v53, v57, s[42:43]
	v_cndmask_b32_e64 v52, v52, v56, s[42:43]

.LBB0_442:
	s_add_i32 s16, s26, 0x90
	v_bitop3_b32 v67, s16, v233, v137 bitop3:0xc8
	v_cndmask_b32_e64 v48, v141, v67, s[44:45]
	v_lshlrev_b32_e32 v196, 8, v48
	v_lshl_add_u64 v[54:55], v[156:157], 0, v[196:197]
	s_and_b64 vcc, exec, s[52:53]
	v_lshl_add_u64 v[58:59], v[154:155], 0, v[196:197]
	s_cbranch_vccnz .LBB0_444
	global_load_dwordx4 v[202:205], v[58:59], off
	global_load_dwordx4 v[206:209], v[54:55], off
	s_waitcnt vmcnt(0)
	v_pk_mul_f32 v[52:53], v[42:43], v[204:205]
	v_pk_mul_f32 v[56:57], v[40:41], v[202:203]
	v_pk_mul_f32 v[50:51], v[46:47], v[204:205]
	v_pk_mul_f32 v[48:49], v[44:45], v[202:203]
	v_pk_fma_f32 v[46:47], v[46:47], v[208:209], v[52:53] neg_lo:[0,0,1] neg_hi:[0,0,1]
	v_pk_fma_f32 v[44:45], v[44:45], v[206:207], v[56:57] neg_lo:[0,0,1] neg_hi:[0,0,1]
	v_pk_fma_f32 v[42:43], v[42:43], v[208:209], v[50:51]
	v_pk_fma_f32 v[40:41], v[40:41], v[206:207], v[48:49]
	v_pk_mul_f32 v[48:49], v[44:45], s[14:15] op_sel_hi:[1,0]
	v_pk_mul_f32 v[50:51], v[46:47], s[14:15] op_sel_hi:[1,0]
	v_pk_mul_f32 v[52:53], v[40:41], s[14:15] op_sel_hi:[1,0]
	v_pk_mul_f32 v[56:57], v[42:43], s[14:15] op_sel_hi:[1,0]
	v_cndmask_b32_e64 v41, v41, v53, s[42:43]
	v_cndmask_b32_e64 v43, v43, v57, s[42:43]
	v_cndmask_b32_e64 v42, v42, v56, s[42:43]
	v_cndmask_b32_e64 v40, v40, v52, s[42:43]
	v_cndmask_b32_e64 v47, v47, v51, s[42:43]
	v_cndmask_b32_e64 v46, v46, v50, s[42:43]
	v_cndmask_b32_e64 v45, v45, v49, s[42:43]
	v_cndmask_b32_e64 v44, v44, v48, s[42:43]

.LBB0_460:
	s_and_b64 vcc, exec, s[52:53]
	s_cbranch_vccnz .LBB0_462
	v_pk_mul_f32 v[54:55], v[34:35], v[204:205]
	v_pk_mul_f32 v[58:59], v[32:33], v[202:203]
	v_pk_mul_f32 v[42:43], v[38:39], v[204:205]
	v_pk_mul_f32 v[40:41], v[36:37], v[202:203]
	v_pk_fma_f32 v[38:39], v[38:39], v[208:209], v[54:55] neg_lo:[0,0,1] neg_hi:[0,0,1]
	v_pk_fma_f32 v[36:37], v[36:37], v[206:207], v[58:59] neg_lo:[0,0,1] neg_hi:[0,0,1]
	v_pk_fma_f32 v[34:35], v[34:35], v[208:209], v[42:43]
	v_pk_fma_f32 v[32:33], v[32:33], v[206:207], v[40:41]
	v_pk_mul_f32 v[40:41], v[36:37], s[14:15] op_sel_hi:[1,0]
	v_pk_mul_f32 v[42:43], v[38:39], s[14:15] op_sel_hi:[1,0]
	v_pk_mul_f32 v[44:45], v[32:33], s[14:15] op_sel_hi:[1,0]
	v_pk_mul_f32 v[46:47], v[34:35], s[14:15] op_sel_hi:[1,0]
	v_cndmask_b32_e64 v33, v33, v45, s[42:43]
	v_cndmask_b32_e64 v35, v35, v47, s[42:43]
	v_cndmask_b32_e64 v34, v34, v46, s[42:43]
	v_cndmask_b32_e64 v32, v32, v44, s[42:43]
	v_cndmask_b32_e64 v39, v39, v43, s[42:43]
	v_cndmask_b32_e64 v38, v38, v42, s[42:43]
	v_cndmask_b32_e64 v37, v37, v41, s[42:43]
	v_cndmask_b32_e64 v36, v36, v40, s[42:43]

.LBB0_468:
	s_add_i32 s16, s26, 0xa0
	v_bitop3_b32 v51, s16, v234, v137 bitop3:0xc8
	v_cndmask_b32_e64 v32, v141, v51, s[44:45]
	v_lshlrev_b32_e32 v196, 8, v32
	v_lshl_add_u64 v[38:39], v[156:157], 0, v[196:197]
	s_and_b64 vcc, exec, s[52:53]
	v_lshl_add_u64 v[42:43], v[154:155], 0, v[196:197]
	s_cbranch_vccnz .LBB0_470
	global_load_dwordx4 v[202:205], v[42:43], off
	global_load_dwordx4 v[206:209], v[38:39], off
	s_waitcnt vmcnt(0)
	v_pk_mul_f32 v[36:37], v[26:27], v[204:205]
	v_pk_mul_f32 v[40:41], v[24:25], v[202:203]
	v_pk_mul_f32 v[34:35], v[30:31], v[204:205]
	v_pk_mul_f32 v[32:33], v[28:29], v[202:203]
	v_pk_fma_f32 v[30:31], v[30:31], v[208:209], v[36:37] neg_lo:[0,0,1] neg_hi:[0,0,1]
	v_pk_fma_f32 v[28:29], v[28:29], v[206:207], v[40:41] neg_lo:[0,0,1] neg_hi:[0,0,1]
	v_pk_fma_f32 v[26:27], v[26:27], v[208:209], v[34:35]
	v_pk_fma_f32 v[24:25], v[24:25], v[206:207], v[32:33]
	v_pk_mul_f32 v[32:33], v[28:29], s[14:15] op_sel_hi:[1,0]
	v_pk_mul_f32 v[34:35], v[30:31], s[14:15] op_sel_hi:[1,0]
	v_pk_mul_f32 v[36:37], v[24:25], s[14:15] op_sel_hi:[1,0]
	v_pk_mul_f32 v[40:41], v[26:27], s[14:15] op_sel_hi:[1,0]
	v_cndmask_b32_e64 v25, v25, v37, s[42:43]
	v_cndmask_b32_e64 v27, v27, v41, s[42:43]
	v_cndmask_b32_e64 v26, v26, v40, s[42:43]
	v_cndmask_b32_e64 v24, v24, v36, s[42:43]
	v_cndmask_b32_e64 v31, v31, v35, s[42:43]
	v_cndmask_b32_e64 v30, v30, v34, s[42:43]
	v_cndmask_b32_e64 v29, v29, v33, s[42:43]
	v_cndmask_b32_e64 v28, v28, v32, s[42:43]

.LBB0_486:
	s_and_b64 vcc, exec, s[52:53]
	s_cbranch_vccnz .LBB0_488
	v_pk_mul_f32 v[38:39], v[18:19], v[204:205]
	v_pk_mul_f32 v[42:43], v[16:17], v[202:203]
	v_pk_mul_f32 v[26:27], v[22:23], v[204:205]
	v_pk_mul_f32 v[24:25], v[20:21], v[202:203]
	v_pk_fma_f32 v[22:23], v[22:23], v[208:209], v[38:39] neg_lo:[0,0,1] neg_hi:[0,0,1]
	v_pk_fma_f32 v[20:21], v[20:21], v[206:207], v[42:43] neg_lo:[0,0,1] neg_hi:[0,0,1]
	v_pk_fma_f32 v[18:19], v[18:19], v[208:209], v[26:27]
	v_pk_fma_f32 v[16:17], v[16:17], v[206:207], v[24:25]
	v_pk_mul_f32 v[24:25], v[20:21], s[14:15] op_sel_hi:[1,0]
	v_pk_mul_f32 v[26:27], v[22:23], s[14:15] op_sel_hi:[1,0]
	v_pk_mul_f32 v[28:29], v[16:17], s[14:15] op_sel_hi:[1,0]
	v_pk_mul_f32 v[30:31], v[18:19], s[14:15] op_sel_hi:[1,0]
	v_cndmask_b32_e64 v17, v17, v29, s[42:43]
	v_cndmask_b32_e64 v19, v19, v31, s[42:43]
	v_cndmask_b32_e64 v18, v18, v30, s[42:43]
	v_cndmask_b32_e64 v16, v16, v28, s[42:43]
	v_cndmask_b32_e64 v23, v23, v27, s[42:43]
	v_cndmask_b32_e64 v22, v22, v26, s[42:43]
	v_cndmask_b32_e64 v21, v21, v25, s[42:43]
	v_cndmask_b32_e64 v20, v20, v24, s[42:43]

.LBB0_494:
	s_addk_i32 s26, 0xb0
	v_bitop3_b32 v35, s26, v235, v137 bitop3:0xc8
	v_cndmask_b32_e64 v16, v141, v35, s[44:45]
	v_lshlrev_b32_e32 v196, 8, v16
	v_lshl_add_u64 v[22:23], v[156:157], 0, v[196:197]
	s_and_b64 vcc, exec, s[52:53]
	v_lshl_add_u64 v[26:27], v[154:155], 0, v[196:197]
	s_cbranch_vccnz .LBB0_496
	global_load_dwordx4 v[202:205], v[26:27], off
	global_load_dwordx4 v[206:209], v[22:23], off
	s_waitcnt vmcnt(0)
	v_pk_mul_f32 v[20:21], v[10:11], v[204:205]
	v_pk_mul_f32 v[24:25], v[8:9], v[202:203]
	v_pk_mul_f32 v[18:19], v[14:15], v[204:205]
	v_pk_mul_f32 v[16:17], v[12:13], v[202:203]
	v_pk_fma_f32 v[14:15], v[14:15], v[208:209], v[20:21] neg_lo:[0,0,1] neg_hi:[0,0,1]
	v_pk_fma_f32 v[12:13], v[12:13], v[206:207], v[24:25] neg_lo:[0,0,1] neg_hi:[0,0,1]
	v_pk_fma_f32 v[10:11], v[10:11], v[208:209], v[18:19]
	v_pk_fma_f32 v[8:9], v[8:9], v[206:207], v[16:17]
	v_pk_mul_f32 v[16:17], v[12:13], s[14:15] op_sel_hi:[1,0]
	v_pk_mul_f32 v[18:19], v[14:15], s[14:15] op_sel_hi:[1,0]
	v_pk_mul_f32 v[20:21], v[8:9], s[14:15] op_sel_hi:[1,0]
	v_pk_mul_f32 v[24:25], v[10:11], s[14:15] op_sel_hi:[1,0]
	v_cndmask_b32_e64 v9, v9, v21, s[42:43]
	v_cndmask_b32_e64 v11, v11, v25, s[42:43]
	v_cndmask_b32_e64 v10, v10, v24, s[42:43]
	v_cndmask_b32_e64 v8, v8, v20, s[42:43]
	v_cndmask_b32_e64 v15, v15, v19, s[42:43]
	v_cndmask_b32_e64 v14, v14, v18, s[42:43]
	v_cndmask_b32_e64 v13, v13, v17, s[42:43]
	v_cndmask_b32_e64 v12, v12, v16, s[42:43]

.LBB0_512:
	s_or_b64 exec, exec, s[2:3]
	s_and_b64 vcc, exec, s[52:53]
	s_cbranch_vccnz .LBB0_514
	v_pk_mul_f32 v[22:23], v[2:3], v[204:205]
	v_pk_mul_f32 v[26:27], v[0:1], v[202:203]
	v_pk_mul_f32 v[10:11], v[6:7], v[204:205]
	v_pk_mul_f32 v[8:9], v[4:5], v[202:203]
	v_pk_fma_f32 v[6:7], v[6:7], v[208:209], v[22:23] neg_lo:[0,0,1] neg_hi:[0,0,1]
	v_pk_fma_f32 v[4:5], v[4:5], v[206:207], v[26:27] neg_lo:[0,0,1] neg_hi:[0,0,1]
	v_pk_fma_f32 v[2:3], v[2:3], v[208:209], v[10:11]
	v_pk_fma_f32 v[0:1], v[0:1], v[206:207], v[8:9]
	v_pk_mul_f32 v[8:9], v[4:5], s[14:15] op_sel_hi:[1,0]
	v_pk_mul_f32 v[10:11], v[6:7], s[14:15] op_sel_hi:[1,0]
	v_pk_mul_f32 v[12:13], v[0:1], s[14:15] op_sel_hi:[1,0]
	v_pk_mul_f32 v[14:15], v[2:3], s[14:15] op_sel_hi:[1,0]
	v_cndmask_b32_e64 v1, v1, v13, s[42:43]
	v_cndmask_b32_e64 v3, v3, v15, s[42:43]
	v_cndmask_b32_e64 v2, v2, v14, s[42:43]
	v_cndmask_b32_e64 v0, v0, v12, s[42:43]
	v_cndmask_b32_e64 v7, v7, v11, s[42:43]
	v_cndmask_b32_e64 v6, v6, v10, s[42:43]
	v_cndmask_b32_e64 v5, v5, v9, s[42:43]
	v_cndmask_b32_e64 v4, v4, v8, s[42:43]
